# router expert sums (6 of 8 chains) and remaining combine wave sums converted from ds_bpermute steps to DPP/permlane ops; counted LDS waits in the router reduction tightened to lgkmcnt(0)
# baseline (speedup 1.0000x reference)
.LBB0_1964:
	s_or_b64 exec, exec, s[4:5]
	v_mov_b32_e32 v19, v20
	v_mov_b32_e32 v23, v21
	v_mov_b32_e32 v20, v132
	v_mov_b32_e32 v21, v38
	v_pk_mul_f32 v[18:19], v[18:19], v[40:41] op_sel_hi:[1,0]
	v_pk_mul_f32 v[2:3], v[2:3], v[40:41] op_sel_hi:[1,0]
	v_pk_mul_f32 v[20:21], v[20:21], v[40:41] op_sel_hi:[1,0]
	s_waitcnt vmcnt(13)
	v_pk_fma_f32 v[18:19], v[94:95], v[18:19], v[98:99]
	v_pk_mul_f32 v[4:5], v[4:5], v[40:41] op_sel_hi:[1,0]
	s_waitcnt vmcnt(6)
	v_pk_fma_f32 v[2:3], v[62:63], v[2:3], v[66:67]
	v_pk_mul_f32 v[14:15], v[14:15], v[40:41] op_sel_hi:[1,0]
	v_pk_fma_f32 v[20:21], v[96:97], v[20:21], v[100:101]
	v_mov_b32_e32 v38, v133
	v_pk_mul_f32 v[22:23], v[22:23], v[40:41] op_sel_hi:[1,0]
	v_pk_fma_f32 v[4:5], v[64:65], v[4:5], v[68:69]
	v_pk_mul_f32 v[6:7], v[6:7], v[40:41] op_sel_hi:[1,0]
	v_pk_mul_f32 v[16:17], v[16:17], v[40:41] op_sel_hi:[1,0]
	s_waitcnt vmcnt(0)
	v_pk_fma_f32 v[14:15], v[34:35], v[14:15], v[42:43]
	v_max_f32_e64 v34, |v18|, |v2|
	v_max_f32_e64 v35, |v19|, |v3|
	v_pk_mul_f32 v[24:25], v[38:39], v[40:41] op_sel_hi:[1,0]
	v_pk_fma_f32 v[22:23], v[86:87], v[22:23], v[90:91]
	v_pk_mul_f32 v[8:9], v[8:9], v[40:41] op_sel_hi:[1,0]
	v_pk_fma_f32 v[6:7], v[54:55], v[6:7], v[58:59]
	v_pk_mul_f32 v[12:13], v[12:13], v[40:41] op_sel_hi:[1,0]
	v_pk_mul_f32 v[10:11], v[10:11], v[40:41] op_sel_hi:[1,0]
	v_pk_fma_f32 v[16:17], v[36:37], v[16:17], v[44:45]
	v_max3_f32 v34, v34, 0, v35
	v_max_f32_e64 v35, |v20|, |v4|
	v_max_f32_e64 v36, |v21|, |v5|
	v_pk_fma_f32 v[24:25], v[88:89], v[24:25], v[92:93]
	v_pk_mul_f32 v[26:27], v[26:27], v[40:41] op_sel_hi:[1,0]
	v_pk_fma_f32 v[8:9], v[56:57], v[8:9], v[60:61]
	v_pk_fma_f32 v[12:13], v[48:49], v[12:13], v[52:53]
	v_pk_fma_f32 v[10:11], v[46:47], v[10:11], v[50:51]
	v_max3_f32 v34, v34, v35, v36
	v_max_f32_e64 v35, |v22|, |v6|
	v_max_f32_e64 v36, |v23|, |v7|
	ds_read_b128 v[50:53], v139
	v_pk_mul_f32 v[28:29], v[28:29], v[40:41] op_sel_hi:[1,0]
	v_pk_fma_f32 v[26:27], v[78:79], v[26:27], v[82:83]
	v_max3_f32 v34, v34, v35, v36
	v_max_f32_e64 v35, |v24|, |v8|
	v_max_f32_e64 v36, |v25|, |v9|
	ds_read_b128 v[54:57], v139 offset:16
	ds_read_b128 v[58:61], v139 offset:32
	ds_read_b128 v[62:65], v139 offset:48
	v_pk_fma_f32 v[28:29], v[80:81], v[28:29], v[84:85]
	v_pk_mul_f32 v[30:31], v[30:31], v[40:41] op_sel_hi:[1,0]
	v_max3_f32 v34, v34, v35, v36
	v_max_f32_e64 v35, |v26|, |v10|
	v_max_f32_e64 v36, |v27|, |v11|
	v_pk_mul_f32 v[32:33], v[32:33], v[40:41] op_sel_hi:[1,0]
	v_pk_fma_f32 v[30:31], v[70:71], v[30:31], v[74:75]
	v_max3_f32 v34, v34, v35, v36
	v_max_f32_e64 v35, |v28|, |v12|
	v_max_f32_e64 v36, |v29|, |v13|
	v_pk_fma_f32 v[32:33], v[72:73], v[32:33], v[76:77]
	v_max3_f32 v34, v34, v35, v36
	v_max_f32_e64 v35, |v30|, |v14|
	v_max_f32_e64 v36, |v31|, |v15|
	v_max3_f32 v34, v34, v35, v36
	v_max_f32_e64 v35, |v32|, |v16|
	v_max_f32_e64 v36, |v33|, |v17|
	s_waitcnt lgkmcnt(3)
	v_fma_f32 v49, v18, v52, 0
	v_fma_f32 v48, v18, v53, 0
	s_waitcnt lgkmcnt(2)
	v_fma_f32 v47, v18, v54, 0
	v_fma_f32 v46, v18, v55, 0
	v_max3_f32 v34, v34, v35, v36
	s_waitcnt lgkmcnt(1)
	v_fmac_f32_e32 v49, v19, v60
	v_fmac_f32_e32 v48, v19, v61
	s_waitcnt lgkmcnt(0)
	v_fmac_f32_e32 v47, v19, v62
	ds_read_b128 v[52:55], v139 offset:64
	v_fmac_f32_e32 v46, v19, v63
	ds_read_b128 v[60:63], v139 offset:80
	v_bfe_u32 v35, v34, 23, 8
	v_and_b32_e32 v34, 0x7fffff, v34
	v_cmp_gt_u32_e32 vcc, s2, v34
	v_fma_f32 v45, v18, v56, 0
	v_fma_f32 v44, v18, v57, 0
	v_cndmask_b32_e64 v34, -2, -3, vcc
	v_add3_u32 v34, v35, v34, s3
	v_fmac_f32_e32 v45, v19, v64
	v_fmac_f32_e32 v44, v19, v65
	v_max_i32_e32 v34, 0xffffff88, v34
	s_waitcnt lgkmcnt(1)
	v_fmac_f32_e32 v49, v20, v54
	v_fmac_f32_e32 v48, v20, v55
	s_waitcnt lgkmcnt(0)
	v_fmac_f32_e32 v47, v20, v60
	v_fmac_f32_e32 v46, v20, v61
	v_fmac_f32_e32 v45, v20, v62
	v_fmac_f32_e32 v44, v20, v63
	ds_read_b128 v[54:57], v139 offset:96
	ds_read_b128 v[60:63], v139 offset:112
	v_add_u32_e32 v34, 0x7f, v34
	v_pk_fma_f32 v[50:51], v[18:19], v[50:51], 0 op_sel_hi:[0,1,0]
	v_lshlrev_b32_e32 v42, 23, v34
	v_mul_lo_u32 v40, v34, s28
	v_cvt_scalef32_2xpk16_fp6_f32 v[34:39], v[18:33], v[2:17], v42
	v_pk_fma_f32 v[18:19], v[18:19], v[58:59], v[50:51] op_sel:[1,0,0]
	s_waitcnt lgkmcnt(1)
	v_fmac_f32_e32 v49, v21, v56
	v_pk_fma_f32 v[18:19], v[20:21], v[52:53], v[18:19] op_sel_hi:[0,1,1]
	v_pk_fma_f32 v[84:85], v[20:21], v[54:55], v[18:19] op_sel:[1,0,0]
	v_fmac_f32_e32 v48, v21, v57
	ds_read_b128 v[50:53], v139 offset:9216
	ds_read_b128 v[54:57], v139 offset:9232
	s_waitcnt lgkmcnt(2)
	v_fmac_f32_e32 v47, v21, v60
	v_fmac_f32_e32 v46, v21, v61
	v_fmac_f32_e32 v45, v21, v62
	v_fmac_f32_e32 v44, v21, v63
	s_waitcnt lgkmcnt(1)
	v_fmac_f32_e32 v49, v22, v52
	v_fmac_f32_e32 v48, v22, v53
	s_waitcnt lgkmcnt(0)
	v_fmac_f32_e32 v47, v22, v54
	ds_read_b128 v[18:21], v139 offset:9248
	v_fmac_f32_e32 v46, v22, v55
	ds_read_b128 v[52:55], v139 offset:9264
	v_fmac_f32_e32 v45, v22, v56
	v_fmac_f32_e32 v44, v22, v57
	ds_read_b128 v[56:59], v139 offset:9280
	ds_read_b128 v[60:63], v139 offset:9296
	s_waitcnt lgkmcnt(3)
	v_fmac_f32_e32 v49, v23, v20
	v_fmac_f32_e32 v48, v23, v21
	s_waitcnt lgkmcnt(2)
	v_fmac_f32_e32 v47, v23, v52
	v_fmac_f32_e32 v46, v23, v53
	v_fmac_f32_e32 v45, v23, v54
	v_fmac_f32_e32 v44, v23, v55
	s_waitcnt lgkmcnt(1)
	v_fmac_f32_e32 v49, v24, v58
	v_fmac_f32_e32 v48, v24, v59
	s_waitcnt lgkmcnt(0)
	v_fmac_f32_e32 v47, v24, v60
	ds_read_b128 v[52:55], v139 offset:9312
	v_fmac_f32_e32 v46, v24, v61
	ds_read_b128 v[58:61], v139 offset:9328
	v_fmac_f32_e32 v45, v24, v62
	v_fmac_f32_e32 v44, v24, v63
	ds_read_b128 v[62:65], v139 offset:18432
	ds_read_b128 v[66:69], v139 offset:18448
	s_waitcnt lgkmcnt(3)
	v_fmac_f32_e32 v49, v25, v54
	v_fmac_f32_e32 v48, v25, v55
	s_waitcnt lgkmcnt(2)
	v_fmac_f32_e32 v47, v25, v58
	v_fmac_f32_e32 v46, v25, v59
	v_fmac_f32_e32 v45, v25, v60
	v_fmac_f32_e32 v44, v25, v61
	s_waitcnt lgkmcnt(1)
	v_fmac_f32_e32 v49, v26, v64
	v_fmac_f32_e32 v48, v26, v65
	s_waitcnt lgkmcnt(0)
	v_fmac_f32_e32 v47, v26, v66
	ds_read_b128 v[58:61], v139 offset:18464
	v_fmac_f32_e32 v46, v26, v67
	ds_read_b128 v[64:67], v139 offset:18480
	v_fmac_f32_e32 v45, v26, v68
	v_fmac_f32_e32 v44, v26, v69
	ds_read_b128 v[68:71], v139 offset:18496
	ds_read_b128 v[72:75], v139 offset:18512
	s_waitcnt lgkmcnt(3)
	v_fmac_f32_e32 v49, v27, v60
	v_fmac_f32_e32 v48, v27, v61
	s_waitcnt lgkmcnt(2)
	v_fmac_f32_e32 v47, v27, v64
	v_fmac_f32_e32 v46, v27, v65
	v_fmac_f32_e32 v45, v27, v66
	v_fmac_f32_e32 v44, v27, v67
	s_waitcnt lgkmcnt(1)
	v_fmac_f32_e32 v49, v28, v70
	v_fmac_f32_e32 v48, v28, v71
	s_waitcnt lgkmcnt(0)
	v_fmac_f32_e32 v47, v28, v72
	ds_read_b128 v[64:67], v139 offset:18528
	v_fmac_f32_e32 v46, v28, v73
	ds_read_b128 v[70:73], v139 offset:18544
	v_fmac_f32_e32 v45, v28, v74
	v_fmac_f32_e32 v44, v28, v75
	ds_read_b128 v[74:77], v139 offset:27648
	ds_read_b128 v[78:81], v139 offset:27664
	s_waitcnt lgkmcnt(3)
	v_fmac_f32_e32 v49, v29, v66
	v_fmac_f32_e32 v48, v29, v67
	s_waitcnt lgkmcnt(2)
	v_fmac_f32_e32 v47, v29, v70
	v_fmac_f32_e32 v46, v29, v71
	v_pk_fma_f32 v[20:21], v[22:23], v[50:51], v[84:85] op_sel_hi:[0,1,1]
	v_fmac_f32_e32 v45, v29, v72
	v_fmac_f32_e32 v44, v29, v73
	s_waitcnt lgkmcnt(1)
	v_fmac_f32_e32 v49, v30, v76
	v_fmac_f32_e32 v48, v30, v77
	s_waitcnt lgkmcnt(0)
	v_fmac_f32_e32 v47, v30, v78
	ds_read_b128 v[70:73], v139 offset:27680
	v_fmac_f32_e32 v46, v30, v79
	ds_read_b128 v[76:79], v139 offset:27696
	v_pk_fma_f32 v[18:19], v[22:23], v[18:19], v[20:21] op_sel:[1,0,0]
	v_fmac_f32_e32 v45, v30, v80
	v_pk_fma_f32 v[18:19], v[24:25], v[56:57], v[18:19] op_sel_hi:[0,1,1]
	v_pk_fma_f32 v[18:19], v[24:25], v[52:53], v[18:19] op_sel:[1,0,0]
	v_fmac_f32_e32 v44, v30, v81
	v_pk_fma_f32 v[18:19], v[26:27], v[62:63], v[18:19] op_sel_hi:[0,1,1]
	v_pk_fma_f32 v[18:19], v[26:27], v[58:59], v[18:19] op_sel:[1,0,0]
	s_waitcnt lgkmcnt(0)
	v_fmac_f32_e32 v47, v31, v76
	v_fmac_f32_e32 v46, v31, v77
	v_fmac_f32_e32 v45, v31, v78
	v_fmac_f32_e32 v44, v31, v79
	ds_read_b128 v[76:79], v139 offset:27712
	ds_read_b128 v[80:83], v139 offset:27728
	v_pk_fma_f32 v[18:19], v[28:29], v[68:69], v[18:19] op_sel_hi:[0,1,1]
	v_pk_fma_f32 v[18:19], v[28:29], v[64:65], v[18:19] op_sel:[1,0,0]
	ds_read_b128 v[22:25], v139 offset:27760
	v_pk_fma_f32 v[18:19], v[30:31], v[74:75], v[18:19] op_sel_hi:[0,1,1]
	v_pk_fma_f32 v[18:19], v[30:31], v[70:71], v[18:19] op_sel:[1,0,0]
	v_fmac_f32_e32 v49, v31, v72
	s_waitcnt lgkmcnt(2)
	v_pk_fma_f32 v[74:75], v[32:33], v[76:77], v[18:19] op_sel_hi:[0,1,1]
	ds_read_b128 v[18:21], v139 offset:27744
	v_fmac_f32_e32 v48, v31, v73
	v_fmac_f32_e32 v49, v32, v78
	v_fmac_f32_e32 v48, v32, v79
	s_waitcnt lgkmcnt(2)
	v_fmac_f32_e32 v47, v32, v80
	v_fmac_f32_e32 v46, v32, v81
	ds_read_b128 v[26:29], v139 offset:36864
	s_waitcnt lgkmcnt(1)
	v_fmac_f32_e32 v49, v33, v20
	v_fmac_f32_e32 v48, v33, v21
	v_fmac_f32_e32 v47, v33, v22
	v_fmac_f32_e32 v46, v33, v23
	ds_read_b128 v[20:23], v139 offset:36880
	v_fmac_f32_e32 v45, v32, v82
	v_fmac_f32_e32 v44, v32, v83
	v_fmac_f32_e32 v45, v33, v24
	v_fmac_f32_e32 v44, v33, v25
	s_waitcnt lgkmcnt(1)
	v_fmac_f32_e32 v49, v2, v28
	v_fmac_f32_e32 v48, v2, v29
	ds_read_b128 v[28:31], v139 offset:36896
	ds_read_b128 v[50:53], v139 offset:36912
	s_waitcnt lgkmcnt(2)
	v_fmac_f32_e32 v47, v2, v20
	v_fmac_f32_e32 v46, v2, v21
	v_fmac_f32_e32 v45, v2, v22
	v_fmac_f32_e32 v44, v2, v23
	ds_read_b128 v[20:23], v139 offset:36928
	ds_read_b128 v[54:57], v139 offset:36944
	s_waitcnt lgkmcnt(3)
	v_fmac_f32_e32 v49, v3, v30
	v_fmac_f32_e32 v48, v3, v31
	s_waitcnt lgkmcnt(2)
	v_fmac_f32_e32 v47, v3, v50
	v_fmac_f32_e32 v46, v3, v51
	v_fmac_f32_e32 v45, v3, v52
	v_fmac_f32_e32 v44, v3, v53
	s_waitcnt lgkmcnt(1)
	v_fmac_f32_e32 v49, v4, v22
	v_fmac_f32_e32 v48, v4, v23
	ds_read_b128 v[22:25], v139 offset:36960
	ds_read_b128 v[50:53], v139 offset:36976
	s_waitcnt lgkmcnt(2)
	v_fmac_f32_e32 v47, v4, v54
	v_fmac_f32_e32 v46, v4, v55
	v_fmac_f32_e32 v45, v4, v56
	v_fmac_f32_e32 v44, v4, v57
	ds_read_b128 v[54:57], v139 offset:46080
	ds_read_b128 v[58:61], v139 offset:46096
	s_waitcnt lgkmcnt(3)
	v_fmac_f32_e32 v49, v5, v24
	v_fmac_f32_e32 v48, v5, v25
	s_waitcnt lgkmcnt(2)
	v_fmac_f32_e32 v47, v5, v50
	v_fmac_f32_e32 v46, v5, v51
	v_fmac_f32_e32 v45, v5, v52
	v_fmac_f32_e32 v44, v5, v53
	s_waitcnt lgkmcnt(1)
	v_fmac_f32_e32 v49, v6, v56
	v_fmac_f32_e32 v48, v6, v57
	s_waitcnt lgkmcnt(0)
	v_fmac_f32_e32 v47, v6, v58
	ds_read_b128 v[50:53], v139 offset:46112
	v_fmac_f32_e32 v46, v6, v59
	ds_read_b128 v[56:59], v139 offset:46128
	v_fmac_f32_e32 v45, v6, v60
	v_fmac_f32_e32 v44, v6, v61
	ds_read_b128 v[60:63], v139 offset:46144
	ds_read_b128 v[64:67], v139 offset:46160
	s_waitcnt lgkmcnt(3)
	v_fmac_f32_e32 v49, v7, v52
	v_fmac_f32_e32 v48, v7, v53
	s_waitcnt lgkmcnt(2)
	v_fmac_f32_e32 v47, v7, v56
	v_fmac_f32_e32 v46, v7, v57
	v_fmac_f32_e32 v45, v7, v58
	v_fmac_f32_e32 v44, v7, v59
	s_waitcnt lgkmcnt(1)
	v_fmac_f32_e32 v49, v8, v62
	v_fmac_f32_e32 v48, v8, v63
	s_waitcnt lgkmcnt(0)
	v_fmac_f32_e32 v47, v8, v64
	ds_read_b128 v[56:59], v139 offset:46176
	v_fmac_f32_e32 v46, v8, v65
	ds_read_b128 v[62:65], v139 offset:46192
	v_pk_fma_f32 v[18:19], v[32:33], v[18:19], v[74:75] op_sel:[1,0,0]
	v_fmac_f32_e32 v45, v8, v66
	v_fmac_f32_e32 v44, v8, v67
	ds_read_b128 v[66:69], v139 offset:55296
	ds_read_b128 v[70:73], v139 offset:55312
	v_pk_fma_f32 v[18:19], v[2:3], v[26:27], v[18:19] op_sel_hi:[0,1,1]
	v_pk_fma_f32 v[2:3], v[2:3], v[28:29], v[18:19] op_sel:[1,0,0]
	s_waitcnt lgkmcnt(3)
	v_fmac_f32_e32 v49, v9, v58
	v_pk_fma_f32 v[2:3], v[4:5], v[20:21], v[2:3] op_sel_hi:[0,1,1]
	v_pk_fma_f32 v[2:3], v[4:5], v[22:23], v[2:3] op_sel:[1,0,0]
	v_fmac_f32_e32 v48, v9, v59
	s_waitcnt lgkmcnt(2)
	v_fmac_f32_e32 v47, v9, v62
	v_fmac_f32_e32 v46, v9, v63
	v_pk_fma_f32 v[2:3], v[6:7], v[54:55], v[2:3] op_sel_hi:[0,1,1]
	v_fmac_f32_e32 v45, v9, v64
	v_fmac_f32_e32 v44, v9, v65
	s_waitcnt lgkmcnt(1)
	v_fmac_f32_e32 v49, v10, v68
	v_fmac_f32_e32 v48, v10, v69
	s_waitcnt lgkmcnt(0)
	v_fmac_f32_e32 v47, v10, v70
	v_fmac_f32_e32 v46, v10, v71
	ds_read_b128 v[62:65], v139 offset:55328
	ds_read_b128 v[68:71], v139 offset:55344
	v_pk_fma_f32 v[2:3], v[6:7], v[50:51], v[2:3] op_sel:[1,0,0]
	ds_read_b128 v[18:21], v139 offset:55392
	v_pk_fma_f32 v[2:3], v[8:9], v[60:61], v[2:3] op_sel_hi:[0,1,1]
	v_pk_fma_f32 v[2:3], v[8:9], v[56:57], v[2:3] op_sel:[1,0,0]
	ds_read_b128 v[6:9], v139 offset:55376
	v_pk_fma_f32 v[2:3], v[10:11], v[66:67], v[2:3] op_sel_hi:[0,1,1]
	s_waitcnt lgkmcnt(3)
	v_pk_fma_f32 v[32:33], v[10:11], v[62:63], v[2:3] op_sel:[1,0,0]
	ds_read_b128 v[2:5], v139 offset:55360
	v_fmac_f32_e32 v49, v11, v64
	v_fmac_f32_e32 v48, v11, v65
	s_waitcnt lgkmcnt(3)
	v_fmac_f32_e32 v47, v11, v68
	v_fmac_f32_e32 v46, v11, v69
	s_waitcnt lgkmcnt(0)
	v_fmac_f32_e32 v49, v12, v4
	v_fmac_f32_e32 v48, v12, v5
	v_fmac_f32_e32 v47, v12, v6
	v_fmac_f32_e32 v46, v12, v7
	ds_read_b128 v[4:7], v139 offset:55408
	v_fmac_f32_e32 v45, v10, v72
	v_fmac_f32_e32 v44, v10, v73
	v_fmac_f32_e32 v45, v11, v70
	v_fmac_f32_e32 v44, v11, v71
	v_fmac_f32_e32 v45, v12, v8
	v_fmac_f32_e32 v44, v12, v9
	v_fmac_f32_e32 v49, v13, v20
	v_fmac_f32_e32 v48, v13, v21
	ds_read_b128 v[8:11], v139 offset:64512
	ds_read_b128 v[20:23], v139 offset:64528
	s_waitcnt lgkmcnt(2)
	v_fmac_f32_e32 v47, v13, v4
	v_fmac_f32_e32 v46, v13, v5
	v_fmac_f32_e32 v45, v13, v6
	v_fmac_f32_e32 v44, v13, v7
	ds_read_b128 v[4:7], v139 offset:64544
	ds_read_b128 v[24:27], v139 offset:64560
	v_pk_fma_f32 v[2:3], v[12:13], v[2:3], v[32:33] op_sel_hi:[0,1,1]
	s_waitcnt lgkmcnt(2)
	v_fmac_f32_e32 v47, v14, v20
	v_fmac_f32_e32 v46, v14, v21
	v_fmac_f32_e32 v45, v14, v22
	v_fmac_f32_e32 v44, v14, v23
	ds_read_b128 v[20:23], v139 offset:64576
	ds_read_b128 v[28:31], v139 offset:64592
	ds_read_b128 v[50:53], v139 offset:64608
	ds_read_b128 v[54:57], v139 offset:64624
	v_pk_fma_f32 v[2:3], v[12:13], v[18:19], v[2:3] op_sel:[1,0,0]
	v_fmac_f32_e32 v49, v14, v10
	v_pk_fma_f32 v[2:3], v[14:15], v[8:9], v[2:3] op_sel_hi:[0,1,1]
	s_waitcnt lgkmcnt(5)
	v_pk_fma_f32 v[2:3], v[14:15], v[4:5], v[2:3] op_sel:[1,0,0]
	v_fmac_f32_e32 v49, v15, v6
	s_waitcnt lgkmcnt(0)
	v_pk_fma_f32 v[2:3], v[16:17], v[20:21], v[2:3] op_sel_hi:[0,1,1]
	s_waitcnt lgkmcnt(0)
	v_pk_fma_f32 v[2:3], v[16:17], v[50:51], v[2:3] op_sel:[1,0,0]
	ds_bpermute_b32 v4, v103, v2
	ds_bpermute_b32 v5, v103, v3
	v_fmac_f32_e32 v49, v16, v22
	v_fmac_f32_e32 v49, v17, v52
	v_fmac_f32_e32 v48, v14, v11
	s_waitcnt lgkmcnt(0)
	v_pk_add_f32 v[2:3], v[2:3], v[4:5]
	ds_bpermute_b32 v4, v134, v2
	ds_bpermute_b32 v5, v134, v3
	s_waitcnt lgkmcnt(0)
	v_add_f32_dpp v6, v49, v49 quad_perm:[1,0,3,2] row_mask:0xf bank_mask:0xf
	v_fmac_f32_e32 v48, v15, v7
	v_fmac_f32_e32 v47, v15, v24
	s_waitcnt lgkmcnt(0)
	v_pk_add_f32 v[2:3], v[2:3], v[4:5]
	ds_bpermute_b32 v4, v135, v2
	ds_bpermute_b32 v5, v135, v3
	v_fmac_f32_e32 v48, v16, v23
	v_fmac_f32_e32 v47, v16, v28
	v_fmac_f32_e32 v48, v17, v53
	v_fmac_f32_e32 v47, v17, v54
	s_waitcnt lgkmcnt(0)
	v_pk_add_f32 v[2:3], v[2:3], v[4:5]
	ds_bpermute_b32 v4, v136, v2
	ds_bpermute_b32 v5, v136, v3
	v_add_f32_dpp v6, v6, v6 quad_perm:[2,3,0,1] row_mask:0xf bank_mask:0xf
	s_waitcnt lgkmcnt(0)
	v_pk_add_f32 v[2:3], v[2:3], v[4:5]
	ds_bpermute_b32 v4, v137, v2
	ds_bpermute_b32 v5, v137, v3
	s_waitcnt lgkmcnt(0)
	v_add_f32_dpp v6, v6, v6 row_half_mirror row_mask:0xf bank_mask:0xf
	s_waitcnt lgkmcnt(0)
	v_add_f32_dpp v7, v47, v47 quad_perm:[1,0,3,2] row_mask:0xf bank_mask:0xf
	v_fmac_f32_e32 v46, v15, v25
	s_waitcnt lgkmcnt(0)
	v_pk_add_f32 v[2:3], v[2:3], v[4:5]
	v_add_f32_dpp v4, v48, v48 quad_perm:[1,0,3,2] row_mask:0xf bank_mask:0xf
	s_waitcnt lgkmcnt(0)
	v_add_f32_dpp v6, v6, v6 row_mirror row_mask:0xf bank_mask:0xf
	v_mov_b32_e32 v11, v6
	s_nop 1
	v_permlane16_swap_b32_e32 v6, v11
	v_fmac_f32_e32 v45, v15, v26
	s_waitcnt lgkmcnt(0)
	v_add_f32_dpp v5, v4, v4 quad_perm:[2,3,0,1] row_mask:0xf bank_mask:0xf
	s_waitcnt lgkmcnt(0)
	v_add_f32_dpp v7, v7, v7 quad_perm:[2,3,0,1] row_mask:0xf bank_mask:0xf
	s_waitcnt lgkmcnt(0)
	v_add_f32_e32 v6, v6, v11
	v_fmac_f32_e32 v44, v15, v27
	v_fmac_f32_e32 v46, v16, v29
	s_waitcnt lgkmcnt(0)
	v_add_f32_dpp v9, v5, v5 row_half_mirror row_mask:0xf bank_mask:0xf
	s_waitcnt lgkmcnt(0)
	v_add_f32_dpp v7, v7, v7 row_half_mirror row_mask:0xf bank_mask:0xf
	v_fmac_f32_e32 v45, v16, v30
	v_fmac_f32_e32 v44, v16, v31
	v_fmac_f32_e32 v46, v17, v55
	s_waitcnt lgkmcnt(0)
	v_add_f32_dpp v9, v9, v9 row_mirror row_mask:0xf bank_mask:0xf
	s_waitcnt lgkmcnt(0)
	v_add_f32_dpp v11, v7, v7 row_mirror row_mask:0xf bank_mask:0xf
	v_mov_b32_e32 v10, v9
	s_nop 1
	v_permlane16_swap_b32_e32 v9, v10
	v_mov_b32_e32 v12, v11
	s_nop 1
	v_permlane16_swap_b32_e32 v11, v12
	v_fmac_f32_e32 v45, v17, v56
	v_fmac_f32_e32 v44, v17, v57
	s_waitcnt lgkmcnt(0)
	v_add_f32_e32 v8, v9, v10
	s_waitcnt lgkmcnt(0)
	v_add_f32_e32 v10, v11, v12
	s_waitcnt lgkmcnt(0)
	v_add_f32_dpp v13, v46, v46 quad_perm:[1,0,3,2] row_mask:0xf bank_mask:0xf
	ds_bpermute_b32 v4, v138, v2
	s_waitcnt lgkmcnt(0)
	v_add_f32_dpp v12, v45, v45 quad_perm:[1,0,3,2] row_mask:0xf bank_mask:0xf
	s_waitcnt lgkmcnt(0)
	v_add_f32_dpp v14, v44, v44 quad_perm:[1,0,3,2] row_mask:0xf bank_mask:0xf
	s_waitcnt lgkmcnt(0)
	v_add_f32_dpp v13, v13, v13 quad_perm:[2,3,0,1] row_mask:0xf bank_mask:0xf
	ds_bpermute_b32 v5, v138, v3
	s_waitcnt lgkmcnt(0)
	v_add_f32_dpp v12, v12, v12 quad_perm:[2,3,0,1] row_mask:0xf bank_mask:0xf
	s_waitcnt lgkmcnt(0)
	v_add_f32_dpp v14, v14, v14 quad_perm:[2,3,0,1] row_mask:0xf bank_mask:0xf
	s_waitcnt lgkmcnt(0)
	v_add_f32_dpp v13, v13, v13 row_half_mirror row_mask:0xf bank_mask:0xf
	v_mov_b32_e32 v7, v6
	s_nop 1
	v_permlane32_swap_b32_e32 v6, v7
	s_waitcnt lgkmcnt(0)
	v_add_f32_dpp v12, v12, v12 row_half_mirror row_mask:0xf bank_mask:0xf
	s_waitcnt lgkmcnt(0)
	v_add_f32_dpp v14, v14, v14 row_half_mirror row_mask:0xf bank_mask:0xf
	s_waitcnt lgkmcnt(0)
	v_add_f32_dpp v13, v13, v13 row_mirror row_mask:0xf bank_mask:0xf
	v_mov_b32_e32 v15, v13
	s_nop 1
	v_permlane16_swap_b32_e32 v13, v15
	v_mov_b32_e32 v9, v8
	s_nop 1
	v_permlane32_swap_b32_e32 v8, v9
	s_waitcnt lgkmcnt(0)
	v_add_f32_dpp v16, v12, v12 row_mirror row_mask:0xf bank_mask:0xf
	s_waitcnt lgkmcnt(0)
	v_add_f32_dpp v17, v14, v14 row_mirror row_mask:0xf bank_mask:0xf
	v_mov_b32_e32 v18, v16
	s_nop 1
	v_permlane16_swap_b32_e32 v16, v18
	v_mov_b32_e32 v19, v17
	s_nop 1
	v_permlane16_swap_b32_e32 v17, v19
	s_waitcnt lgkmcnt(0)
	v_add_f32_e32 v12, v13, v15
	v_mov_b32_e32 v11, v10
	s_nop 1
	v_permlane32_swap_b32_e32 v10, v11
	v_mov_b32_e32 v13, v12
	s_nop 1
	v_permlane32_swap_b32_e32 v12, v13
	s_waitcnt lgkmcnt(0)
	v_add_f32_e32 v14, v16, v18
	s_waitcnt lgkmcnt(0)
	v_add_f32_e32 v16, v17, v19
	v_mov_b32_e32 v15, v14
	s_nop 1
	v_permlane32_swap_b32_e32 v14, v15
	v_mov_b32_e32 v17, v16
	s_nop 1
	v_permlane32_swap_b32_e32 v16, v17
	v_lshl_add_u64 v[42:43], s[72:73], 0, v[130:131]
	v_add_co_u32_e32 v42, vcc, s29, v42
	s_nop 1
	v_addc_co_u32_e32 v43, vcc, 0, v43, vcc
	global_store_dwordx4 v[42:43], v[34:37], off
	global_store_dwordx4 v[42:43], v[38:41], off offset:64
	s_and_saveexec_b64 s[50:51], s[8:9]
	s_cbranch_execz .LBB0_1961
	v_pk_add_f32 v[2:3], v[2:3], v[4:5]
	v_add_f32_e32 v6, v6, v7
	v_cmp_gt_f32_e32 vcc, v3, v2
	v_add_f32_e32 v8, v8, v9
	s_waitcnt lgkmcnt(0)
	v_add_f32_e32 v10, v10, v11
	v_cndmask_b32_e32 v4, v2, v3, vcc
	v_cmp_gt_f32_e64 s[10:11], v6, v4
	s_waitcnt lgkmcnt(0)
	v_add_f32_e32 v12, v12, v13
	s_waitcnt lgkmcnt(0)
	v_add_f32_e32 v14, v14, v15
	v_cndmask_b32_e64 v4, v4, v6, s[10:11]
	v_cmp_gt_f32_e64 s[12:13], v8, v4
	s_waitcnt lgkmcnt(0)
	v_add_f32_e32 v16, v16, v17
	v_cmp_nlt_f32_e64 s[24:25], s33, v2
	v_cndmask_b32_e64 v4, v4, v8, s[12:13]
	v_cmp_gt_f32_e64 s[14:15], v10, v4
	s_nop 1
	v_cndmask_b32_e64 v4, v4, v10, s[14:15]
	v_cmp_gt_f32_e64 s[16:17], v12, v4
	s_nop 1
	v_cndmask_b32_e64 v4, v4, v12, s[16:17]
	v_cmp_gt_f32_e64 s[18:19], v14, v4
	s_nop 1
	v_cndmask_b32_e64 v5, v4, v14, s[18:19]
	v_cndmask_b32_e64 v4, 0, 1, vcc
	v_cndmask_b32_e64 v4, v4, 2, s[10:11]
	v_cndmask_b32_e64 v4, v4, 3, s[12:13]
	v_cndmask_b32_e64 v4, v4, 4, s[14:15]
	v_cndmask_b32_e64 v4, v4, 5, s[16:17]
	v_cndmask_b32_e64 v4, v4, 6, s[18:19]
	v_cmp_ngt_f32_e32 vcc, v16, v5
	s_nop 1
	v_cndmask_b32_e32 v4, 7, v4, vcc
	v_cmp_eq_u32_e64 s[22:23], 0, v4
	s_or_b64 s[22:23], s[24:25], s[22:23]
	v_cmp_ne_u32_e64 s[20:21], 1, v4
	v_cndmask_b32_e64 v2, v2, v142, s[22:23]
	v_cmp_gt_f32_e64 s[24:25], v3, v2
	s_and_b64 s[20:21], s[20:21], s[24:25]
	v_cndmask_b32_e64 v2, v2, v3, s[20:21]
	v_cmp_ne_u32_e64 s[18:19], 2, v4
	v_cmp_gt_f32_e64 s[24:25], v6, v2
	s_and_b64 s[18:19], s[18:19], s[24:25]
	v_cndmask_b32_e64 v2, v2, v6, s[18:19]
	v_cmp_ne_u32_e64 s[16:17], 3, v4
	v_cmp_gt_f32_e64 s[24:25], v8, v2
	s_and_b64 s[16:17], s[16:17], s[24:25]
	v_cndmask_b32_e64 v2, v2, v8, s[16:17]
	v_cmp_ne_u32_e64 s[14:15], 4, v4
	v_cmp_gt_f32_e64 s[24:25], v10, v2
	s_and_b64 s[14:15], s[14:15], s[24:25]
	v_cndmask_b32_e64 v2, v2, v10, s[14:15]
	v_cmp_ne_u32_e64 s[12:13], 5, v4
	v_cmp_gt_f32_e64 s[24:25], v12, v2
	s_and_b64 s[12:13], s[12:13], s[24:25]
	v_cndmask_b32_e64 v2, v2, v12, s[12:13]
	v_cmp_ne_u32_e64 s[10:11], 6, v4
	v_cmp_gt_f32_e64 s[24:25], v14, v2
	s_and_b64 s[10:11], s[10:11], s[24:25]
	v_cndmask_b32_e64 v2, v2, v14, s[10:11]
	v_cmp_gt_f32_e64 s[24:25], v16, v2
	s_and_b64 s[24:25], vcc, s[24:25]
	v_cndmask_b32_e32 v3, v16, v5, vcc
	v_cndmask_b32_e64 v2, v2, v16, s[24:25]
	v_sub_f32_e32 v2, v2, v3
	v_mul_f32_e32 v2, 0x3fb8aa3b, v2
	v_exp_f32_e32 v2, v2
	v_cndmask_b32_e64 v3, 0, -1, s[22:23]
	v_cndmask_b32_e64 v3, v3, 1, s[20:21]
	v_cndmask_b32_e64 v3, v3, 2, s[18:19]
	v_add_f32_e32 v6, 1.0, v2
	v_div_scale_f32 v7, s[4:5], v6, v6, v2
	v_cndmask_b32_e64 v3, v3, 3, s[16:17]
	v_rcp_f32_e32 v8, v7
	v_cndmask_b32_e64 v3, v3, 4, s[14:15]
	v_cndmask_b32_e64 v3, v3, 5, s[12:13]
	v_cndmask_b32_e64 v3, v3, 6, s[10:11]
	v_cndmask_b32_e64 v5, v3, 7, s[24:25]
	v_fma_f32 v3, -v7, v8, 1.0
	v_fmac_f32_e32 v8, v3, v8
	v_div_scale_f32 v3, vcc, v2, v6, v2
	v_mul_f32_e32 v9, v3, v8
	v_fma_f32 v10, -v7, v9, v3
	v_fmac_f32_e32 v9, v10, v8
	v_fma_f32 v3, -v7, v9, v3
	v_div_scale_f32 v7, s[4:5], v6, v6, 1.0
	v_rcp_f32_e32 v10, v7
	v_div_fmas_f32 v3, v3, v8, v9
	v_div_fixup_f32 v11, v3, v6, v2
	v_fma_f32 v2, -v7, v10, 1.0
	v_fmac_f32_e32 v10, v2, v10
	v_div_scale_f32 v2, vcc, 1.0, v6, 1.0
	v_mul_f32_e32 v3, v2, v10
	v_fma_f32 v8, -v7, v3, v2
	v_fmac_f32_e32 v3, v8, v10
	v_fma_f32 v2, -v7, v3, v2
	v_div_fmas_f32 v2, v2, v10, v3
	v_div_fixup_f32 v10, v2, v6, 1.0
	v_lshlrev_b64 v[2:3], 2, v[126:127]
	v_add_u32_e32 v8, 1, v126
	v_lshl_add_u64 v[6:7], s[36:37], 0, v[2:3]
	v_ashrrev_i32_e32 v9, 31, v8
	v_lshl_add_u64 v[2:3], s[38:39], 0, v[2:3]
	global_store_dword v[2:3], v10, off
	v_lshl_add_u64 v[2:3], v[8:9], 2, s[38:39]
	global_store_dwordx2 v[6:7], v[4:5], off
	global_store_dword v[2:3], v11, off
	v_lshl_add_u32 v2, v4, 2, s40
	ds_add_u32 v2, v141
	v_lshl_add_u32 v2, v5, 2, s40
	ds_add_u32 v2, v141
	s_branch .LBB0_1961

.LBB0_2372:
	s_or_b64 exec, exec, s[16:17]
	v_sub_f32_e32 v21, v21, v232
	v_sub_f32_e32 v20, v20, v232
	v_sub_f32_e32 v23, v23, v232
	v_sub_f32_e32 v22, v22, v232
	v_sub_f32_e32 v11, v11, v232
	v_sub_f32_e32 v10, v10, v232
	v_pk_mul_f32 v[22:23], v[150:151], v[22:23] op_sel_hi:[0,1]
	v_pk_mul_f32 v[20:21], v[150:151], v[20:21] op_sel_hi:[0,1]
	v_sub_f32_e32 v9, v9, v232
	v_sub_f32_e32 v8, v8, v232
	v_pk_mul_f32 v[10:11], v[150:151], v[10:11] op_sel_hi:[0,1]
	v_pk_fma_f32 v[16:17], v[12:13], v[20:21], v[16:17]
	v_pk_fma_f32 v[12:13], v[14:15], v[22:23], v[18:19]
	v_pk_mul_f32 v[14:15], v[148:149], v[172:173] op_sel_hi:[0,1]
	v_pk_mul_f32 v[18:19], v[148:149], v[170:171] op_sel_hi:[0,1]
	v_pk_mul_f32 v[8:9], v[150:151], v[8:9] op_sel_hi:[0,1]
	v_pk_fma_f32 v[2:3], v[2:3], v[10:11], v[6:7]
	v_pk_mul_f32 v[6:7], v[148:149], v[158:159] op_sel_hi:[0,1]
	v_sub_f32_e32 v33, v33, v232
	v_sub_f32_e32 v32, v32, v232
	v_sub_f32_e32 v35, v35, v232
	v_sub_f32_e32 v34, v34, v232
	v_pk_fma_f32 v[18:19], v[152:153], v[164:165], v[18:19] op_sel_hi:[0,1,1]
	v_pk_fma_f32 v[14:15], v[152:153], v[166:167], v[14:15] op_sel_hi:[0,1,1]
	v_pk_fma_f32 v[0:1], v[0:1], v[8:9], v[4:5]
	v_pk_mul_f32 v[4:5], v[148:149], v[160:161] op_sel_hi:[0,1]
	v_pk_fma_f32 v[6:7], v[152:153], v[154:155], v[6:7] op_sel_hi:[0,1,1]
	v_pk_mul_f32 v[34:35], v[150:151], v[34:35] op_sel_hi:[0,1]
	v_pk_mul_f32 v[32:33], v[150:151], v[32:33] op_sel_hi:[0,1]
	v_pk_fma_f32 v[12:13], v[12:13], s[14:15], v[14:15] op_sel_hi:[1,0,1]
	v_pk_fma_f32 v[14:15], v[16:17], s[14:15], v[18:19] op_sel_hi:[1,0,1]
	v_pk_fma_f32 v[4:5], v[152:153], v[156:157], v[4:5] op_sel_hi:[0,1,1]
	v_pk_fma_f32 v[6:7], v[0:1], s[14:15], v[6:7] op_sel_hi:[1,0,1]
	v_pk_fma_f32 v[28:29], v[24:25], v[32:33], v[28:29]
	v_pk_fma_f32 v[24:25], v[26:27], v[34:35], v[30:31]
	v_pk_mul_f32 v[26:27], v[148:149], v[184:185] op_sel_hi:[0,1]
	v_pk_mul_f32 v[30:31], v[148:149], v[182:183] op_sel_hi:[0,1]
	v_pk_fma_f32 v[4:5], v[2:3], s[14:15], v[4:5] op_sel_hi:[1,0,1]
	v_mov_b32_e32 v8, v6
	v_mov_b32_e32 v9, v14
	v_mov_b32_e32 v10, v7
	v_mov_b32_e32 v11, v15
	v_sub_f32_e32 v57, v57, v232
	v_sub_f32_e32 v56, v56, v232
	v_sub_f32_e32 v59, v59, v232
	v_sub_f32_e32 v58, v58, v232
	v_sub_f32_e32 v45, v45, v232
	v_sub_f32_e32 v44, v44, v232
	v_sub_f32_e32 v47, v47, v232
	v_sub_f32_e32 v46, v46, v232
	v_pk_fma_f32 v[30:31], v[152:153], v[178:179], v[30:31] op_sel_hi:[0,1,1]
	v_pk_fma_f32 v[26:27], v[152:153], v[180:181], v[26:27] op_sel_hi:[0,1,1]
	v_pk_add_f32 v[8:9], v[8:9], v[10:11]
	v_mov_b32_e32 v10, v4
	v_mov_b32_e32 v11, v12
	v_mov_b32_e32 v16, v5
	v_mov_b32_e32 v17, v13
	v_pk_mul_f32 v[58:59], v[150:151], v[58:59] op_sel_hi:[0,1]
	v_pk_mul_f32 v[56:57], v[150:151], v[56:57] op_sel_hi:[0,1]
	v_pk_mul_f32 v[46:47], v[150:151], v[46:47] op_sel_hi:[0,1]
	v_pk_mul_f32 v[44:45], v[150:151], v[44:45] op_sel_hi:[0,1]
	v_pk_fma_f32 v[24:25], v[24:25], s[14:15], v[26:27] op_sel_hi:[1,0,1]
	v_pk_fma_f32 v[26:27], v[28:29], s[14:15], v[30:31] op_sel_hi:[1,0,1]
	v_pk_add_f32 v[10:11], v[10:11], v[16:17]
	v_sub_f32_e32 v81, v81, v232
	v_sub_f32_e32 v80, v80, v232
	v_sub_f32_e32 v83, v83, v232
	v_sub_f32_e32 v82, v82, v232
	v_sub_f32_e32 v69, v69, v232
	v_sub_f32_e32 v68, v68, v232
	v_sub_f32_e32 v71, v71, v232
	v_sub_f32_e32 v70, v70, v232
	v_pk_fma_f32 v[52:53], v[48:49], v[56:57], v[52:53]
	v_pk_fma_f32 v[48:49], v[50:51], v[58:59], v[54:55]
	v_pk_mul_f32 v[50:51], v[148:149], v[200:201] op_sel_hi:[0,1]
	v_pk_mul_f32 v[54:55], v[148:149], v[198:199] op_sel_hi:[0,1]
	v_pk_fma_f32 v[40:41], v[36:37], v[44:45], v[40:41]
	v_pk_fma_f32 v[36:37], v[38:39], v[46:47], v[42:43]
	v_pk_mul_f32 v[38:39], v[148:149], v[192:193] op_sel_hi:[0,1]
	v_pk_mul_f32 v[42:43], v[148:149], v[190:191] op_sel_hi:[0,1]
	v_pk_add_f32 v[8:9], v[8:9], v[10:11]
	v_pk_mov_b32 v[10:11], v[26:27], v[24:25] op_sel:[1,0]
	v_mov_b32_e32 v16, v26
	v_mov_b32_e32 v17, v25
	v_pk_mul_f32 v[82:83], v[150:151], v[82:83] op_sel_hi:[0,1]
	v_pk_mul_f32 v[80:81], v[150:151], v[80:81] op_sel_hi:[0,1]
	v_pk_mul_f32 v[70:71], v[150:151], v[70:71] op_sel_hi:[0,1]
	v_pk_mul_f32 v[68:69], v[150:151], v[68:69] op_sel_hi:[0,1]
	v_pk_fma_f32 v[54:55], v[152:153], v[194:195], v[54:55] op_sel_hi:[0,1,1]
	v_pk_fma_f32 v[50:51], v[152:153], v[196:197], v[50:51] op_sel_hi:[0,1,1]
	v_pk_fma_f32 v[42:43], v[152:153], v[186:187], v[42:43] op_sel_hi:[0,1,1]
	v_pk_fma_f32 v[38:39], v[152:153], v[188:189], v[38:39] op_sel_hi:[0,1,1]
	v_pk_add_f32 v[10:11], v[10:11], v[16:17]
	v_pk_fma_f32 v[76:77], v[72:73], v[80:81], v[76:77]
	v_pk_fma_f32 v[72:73], v[74:75], v[82:83], v[78:79]
	v_pk_mul_f32 v[74:75], v[148:149], v[216:217] op_sel_hi:[0,1]
	v_pk_mul_f32 v[78:79], v[148:149], v[214:215] op_sel_hi:[0,1]
	v_pk_fma_f32 v[64:65], v[60:61], v[68:69], v[64:65]
	v_pk_fma_f32 v[60:61], v[62:63], v[70:71], v[66:67]
	v_pk_mul_f32 v[62:63], v[148:149], v[208:209] op_sel_hi:[0,1]
	v_pk_mul_f32 v[66:67], v[148:149], v[206:207] op_sel_hi:[0,1]
	v_pk_fma_f32 v[48:49], v[48:49], s[14:15], v[50:51] op_sel_hi:[1,0,1]
	v_pk_fma_f32 v[50:51], v[52:53], s[14:15], v[54:55] op_sel_hi:[1,0,1]
	v_pk_fma_f32 v[36:37], v[36:37], s[14:15], v[38:39] op_sel_hi:[1,0,1]
	v_pk_fma_f32 v[38:39], v[40:41], s[14:15], v[42:43] op_sel_hi:[1,0,1]
	v_add_f32_e32 v8, 0, v8
	v_pk_add_f32 v[10:11], v[10:11], v[10:11] op_sel:[0,1] op_sel_hi:[1,0]
	v_pk_fma_f32 v[78:79], v[152:153], v[210:211], v[78:79] op_sel_hi:[0,1,1]
	v_pk_fma_f32 v[74:75], v[152:153], v[212:213], v[74:75] op_sel_hi:[0,1,1]
	v_pk_fma_f32 v[66:67], v[152:153], v[202:203], v[66:67] op_sel_hi:[0,1,1]
	v_pk_fma_f32 v[62:63], v[152:153], v[204:205], v[62:63] op_sel_hi:[0,1,1]
	v_add_f32_e32 v8, v8, v9
	v_add_f32_e32 v16, v38, v39
	v_add_f32_e32 v18, v36, v37
	v_mov_b32_e32 v9, v50
	v_mov_b32_e32 v11, v51
	v_mov_b32_e32 v17, v48
	v_mov_b32_e32 v19, v49
	v_pk_fma_f32 v[72:73], v[72:73], s[14:15], v[74:75] op_sel_hi:[1,0,1]
	v_pk_fma_f32 v[74:75], v[76:77], s[14:15], v[78:79] op_sel_hi:[1,0,1]
	s_waitcnt vmcnt(0)
	v_sub_f32_e32 v77, v93, v232
	v_sub_f32_e32 v76, v92, v232
	v_sub_f32_e32 v79, v95, v232
	v_sub_f32_e32 v78, v94, v232
	v_pk_fma_f32 v[60:61], v[60:61], s[14:15], v[62:63] op_sel_hi:[1,0,1]
	v_pk_fma_f32 v[62:63], v[64:65], s[14:15], v[66:67] op_sel_hi:[1,0,1]
	v_pk_add_f32 v[8:9], v[8:9], v[10:11]
	v_pk_add_f32 v[10:11], v[16:17], v[18:19]
	v_pk_mul_f32 v[78:79], v[150:151], v[78:79] op_sel_hi:[0,1]
	v_pk_mul_f32 v[76:77], v[150:151], v[76:77] op_sel_hi:[0,1]
	v_pk_mul_f32 v[0:1], v[148:149], v[224:225] op_sel_hi:[0,1]
	v_pk_mul_f32 v[2:3], v[148:149], v[222:223] op_sel_hi:[0,1]
	v_pk_add_f32 v[8:9], v[8:9], v[10:11]
	v_pk_mov_b32 v[10:11], v[62:63], v[60:61] op_sel:[1,0]
	v_mov_b32_e32 v16, v62
	v_mov_b32_e32 v17, v61
	v_pk_fma_f32 v[76:77], v[84:85], v[76:77], v[88:89]
	v_pk_fma_f32 v[78:79], v[86:87], v[78:79], v[90:91]
	v_pk_fma_f32 v[2:3], v[152:153], v[218:219], v[2:3] op_sel_hi:[0,1,1]
	v_pk_fma_f32 v[0:1], v[152:153], v[220:221], v[0:1] op_sel_hi:[0,1,1]
	v_pk_add_f32 v[10:11], v[10:11], v[16:17]
	v_pk_fma_f32 v[0:1], v[78:79], s[14:15], v[0:1] op_sel_hi:[1,0,1]
	v_pk_fma_f32 v[2:3], v[76:77], s[14:15], v[2:3] op_sel_hi:[1,0,1]
	v_pk_add_f32 v[8:9], v[8:9], v[8:9] op_sel:[0,1] op_sel_hi:[1,0]
	v_pk_add_f32 v[10:11], v[10:11], v[10:11] op_sel:[0,1] op_sel_hi:[1,0]
	v_add_f32_e32 v16, v74, v75
	v_add_f32_e32 v18, v72, v73
	v_mov_b32_e32 v9, v2
	v_mov_b32_e32 v11, v3
	v_mov_b32_e32 v17, v0
	v_mov_b32_e32 v19, v1
	v_pk_add_f32 v[8:9], v[8:9], v[10:11]
	v_pk_add_f32 v[10:11], v[16:17], v[18:19]
	v_lshlrev_b64 v[154:155], 11, v[96:97]
	v_pk_add_f32 v[8:9], v[8:9], v[10:11]
	v_add_u32_e32 v96, s22, v96
	v_add_f32_e32 v8, v8, v9
	s_waitcnt lgkmcnt(0)
	s_nop 1
	v_add_f32_dpp v8, v8, v8 quad_perm:[1,0,3,2] row_mask:0xf bank_mask:0xf
	s_nop 1
	v_add_f32_dpp v8, v8, v8 quad_perm:[2,3,0,1] row_mask:0xf bank_mask:0xf
	s_nop 1
	v_add_f32_dpp v8, v8, v8 row_half_mirror row_mask:0xf bank_mask:0xf
	s_nop 1
	v_add_f32_dpp v8, v8, v8 row_mirror row_mask:0xf bank_mask:0xf
	v_mov_b32_e32 v9, v8
	s_nop 1
	v_permlane16_swap_b32_e32 v8, v9
	v_add_f32_e32 v8, v8, v9
	v_mov_b32_e32 v9, v8
	s_nop 1
	v_permlane32_swap_b32_e32 v8, v9
	v_add_f32_e32 v20, v8, v9
	v_fmamk_f32 v7, v20, 0xba000000, v7
	v_fmamk_f32 v15, v20, 0xba000000, v15
	v_fmamk_f32 v5, v20, 0xba000000, v5
	v_fmac_f32_e32 v6, 0xba000000, v20
	v_fmamk_f32 v13, v20, 0xba000000, v13
	v_fmac_f32_e32 v14, 0xba000000, v20
	v_mov_b32_e32 v10, v7
	v_mov_b32_e32 v11, v15
	v_fmac_f32_e32 v4, 0xba000000, v20
	v_fmac_f32_e32 v12, 0xba000000, v20
	v_mov_b32_e32 v8, v6
	v_mov_b32_e32 v9, v14
	v_pk_mul_f32 v[10:11], v[10:11], v[10:11]
	v_mov_b32_e32 v16, v5
	v_mov_b32_e32 v17, v13
	v_pk_fma_f32 v[8:9], v[8:9], v[8:9], v[10:11]
	v_mov_b32_e32 v10, v4
	v_mov_b32_e32 v11, v12
	v_pk_mul_f32 v[16:17], v[16:17], v[16:17]
	v_fmamk_f32 v27, v20, 0xba000000, v27
	v_pk_fma_f32 v[10:11], v[10:11], v[10:11], v[16:17]
	v_fmac_f32_e32 v26, 0xba000000, v20
	v_pk_add_f32 v[8:9], v[8:9], v[10:11]
	v_fmamk_f32 v25, v20, 0xba000000, v25
	v_fmac_f32_e32 v24, 0xba000000, v20
	v_pk_add_f32 v[8:9], v[8:9], v[8:9] op_sel_hi:[0,1]
	v_pk_mul_f32 v[10:11], v[24:25], v[24:25]
	v_pk_mul_f32 v[16:17], v[26:27], v[26:27]
	v_fmac_f32_e32 v38, 0xba000000, v20
	v_pk_mov_b32 v[18:19], v[16:17], v[10:11] op_sel:[1,0]
	v_mov_b32_e32 v17, v11
	v_fmamk_f32 v39, v20, 0xba000000, v39
	v_fmac_f32_e32 v36, 0xba000000, v20
	v_mul_f32_e32 v8, v38, v38
	v_pk_add_f32 v[10:11], v[18:19], v[16:17]
	v_fmamk_f32 v37, v20, 0xba000000, v37
	v_pk_fma_f32 v[16:17], v[38:39], v[38:39], v[8:9] op_sel_hi:[1,1,0]
	v_mul_f32_e32 v8, v36, v36
	v_pk_add_f32 v[10:11], v[10:11], v[10:11] op_sel_hi:[0,1]
	v_pk_fma_f32 v[18:19], v[36:37], v[36:37], v[8:9] op_sel_hi:[1,1,0]
	v_fmamk_f32 v49, v20, 0xba000000, v49
	v_fmac_f32_e32 v48, 0xba000000, v20
	v_fmamk_f32 v51, v20, 0xba000000, v51
	v_fmac_f32_e32 v50, 0xba000000, v20
	v_mul_f32_e32 v16, v50, v50
	v_mul_f32_e32 v18, v51, v51
	v_mul_f32_e32 v10, v48, v48
	v_mul_f32_e32 v8, v49, v49
	v_pk_add_f32 v[16:17], v[16:17], v[18:19]
	v_pk_add_f32 v[8:9], v[10:11], v[8:9]
	v_fmamk_f32 v63, v20, 0xba000000, v63
	v_pk_add_f32 v[8:9], v[16:17], v[8:9]
	v_fmac_f32_e32 v62, 0xba000000, v20
	v_fmamk_f32 v61, v20, 0xba000000, v61
	v_fmac_f32_e32 v60, 0xba000000, v20
	v_pk_add_f32 v[8:9], v[8:9], v[8:9] op_sel_hi:[0,1]
	v_pk_mul_f32 v[10:11], v[60:61], v[60:61]
	v_pk_mul_f32 v[16:17], v[62:63], v[62:63]
	v_fmac_f32_e32 v74, 0xba000000, v20
	v_pk_mov_b32 v[18:19], v[16:17], v[10:11] op_sel:[1,0]
	v_mov_b32_e32 v17, v11
	v_fmamk_f32 v75, v20, 0xba000000, v75
	v_fmac_f32_e32 v72, 0xba000000, v20
	v_mul_f32_e32 v8, v74, v74
	v_pk_add_f32 v[10:11], v[18:19], v[16:17]
	v_fmamk_f32 v73, v20, 0xba000000, v73
	v_pk_fma_f32 v[16:17], v[74:75], v[74:75], v[8:9] op_sel_hi:[1,1,0]
	v_mul_f32_e32 v8, v72, v72
	v_pk_add_f32 v[10:11], v[10:11], v[10:11] op_sel_hi:[0,1]
	v_pk_fma_f32 v[18:19], v[72:73], v[72:73], v[8:9] op_sel_hi:[1,1,0]
	v_fmamk_f32 v1, v20, 0xba000000, v1
	v_fmac_f32_e32 v0, 0xba000000, v20
	v_fmamk_f32 v3, v20, 0xba000000, v3
	v_fmac_f32_e32 v2, 0xba000000, v20
	v_mul_f32_e32 v16, v2, v2
	v_mul_f32_e32 v18, v3, v3
	v_mul_f32_e32 v10, v0, v0
	v_mul_f32_e32 v8, v1, v1
	v_pk_add_f32 v[16:17], v[16:17], v[18:19]
	v_pk_add_f32 v[8:9], v[10:11], v[8:9]
	s_nop 0
	v_pk_add_f32 v[8:9], v[16:17], v[8:9]
	s_nop 0
	v_add_f32_e32 v20, v8, v9
	global_load_dwordx4 v[8:11], v[106:107], off
	global_load_dwordx4 v[16:19], v[108:109], off
	s_waitcnt lgkmcnt(0)
	v_add_f32_dpp v44, v20, v20 quad_perm:[1,0,3,2] row_mask:0xf bank_mask:0xf
	global_load_dwordx4 v[20:23], v[106:107], off offset:1024
	global_load_dwordx4 v[28:31], v[108:109], off offset:1024
	global_load_dwordx4 v[32:35], v[106:107], off offset:2048
	global_load_dwordx4 v[40:43], v[108:109], off offset:2048
	s_waitcnt lgkmcnt(0)
	v_add_f32_dpp v68, v44, v44 quad_perm:[2,3,0,1] row_mask:0xf bank_mask:0xf
	global_load_dwordx4 v[44:47], v[106:107], off offset:3072
	global_load_dwordx4 v[52:55], v[108:109], off offset:3072
	global_load_dwordx4 v[56:59], v[110:111], off
	global_load_dwordx4 v[64:67], v[112:113], off
	s_waitcnt lgkmcnt(0)
	v_add_f32_dpp v88, v68, v68 row_half_mirror row_mask:0xf bank_mask:0xf
	global_load_dwordx4 v[68:71], v[114:115], off
	global_load_dwordx4 v[76:79], v[116:117], off
	global_load_dwordx4 v[80:83], v[118:119], off
	global_load_dwordx4 v[84:87], v[120:121], off
	s_waitcnt lgkmcnt(0)
	v_add_f32_dpp v98, v88, v88 row_mirror row_mask:0xf bank_mask:0xf
	global_load_dwordx4 v[88:91], v[122:123], off
	global_load_dwordx4 v[92:95], v[124:125], off
	v_mov_b32_e32 v148, v98
	s_nop 1
	v_permlane16_swap_b32_e32 v98, v148
	s_waitcnt lgkmcnt(0)
	v_add_f32_e32 v98, v98, v148
	v_mov_b32_e32 v148, v98
	s_nop 1
	v_permlane32_swap_b32_e32 v98, v148
	s_waitcnt lgkmcnt(0)
	v_add_f32_e32 v98, v98, v148
	v_fmamk_f32 v98, v98, 0x3a000000, v229
	v_mul_f32_e32 v148, 0x4f800000, v98
	v_cmp_gt_f32_e32 vcc, s28, v98
	s_nop 1
	v_cndmask_b32_e32 v98, v98, v148, vcc
	v_sqrt_f32_e32 v148, v98
	s_nop 0
	v_add_u32_e32 v150, -1, v148
	v_fma_f32 v152, -v150, v148, v98
	v_cmp_ge_f32_e64 s[0:1], 0, v152
	v_add_u32_e32 v152, 1, v148
	s_nop 0
	v_cndmask_b32_e64 v150, v148, v150, s[0:1]
	v_fma_f32 v148, -v152, v148, v98
	v_cmp_lt_f32_e64 s[0:1], 0, v148
	s_nop 1
	v_cndmask_b32_e64 v148, v150, v152, s[0:1]
	v_mul_f32_e32 v150, 0x37800000, v148
	v_cndmask_b32_e32 v148, v148, v150, vcc
	v_cmp_class_f32_e32 vcc, v98, v230
	s_nop 1
	v_cndmask_b32_e32 v98, v148, v98, vcc
	v_div_scale_f32 v148, s[0:1], v98, v98, 1.0
	v_rcp_f32_e32 v150, v148
	s_nop 0
	v_fma_f32 v97, -v148, v150, 1.0
	v_fmac_f32_e32 v150, v97, v150
	v_div_scale_f32 v97, vcc, 1.0, v98, 1.0
	v_mul_f32_e32 v152, v97, v150
	v_fma_f32 v156, -v148, v152, v97
	v_fmac_f32_e32 v152, v156, v150
	v_fma_f32 v97, -v148, v152, v97
	v_div_fmas_f32 v97, v97, v150, v152
	v_div_fixup_f32 v98, v97, v98, 1.0
	v_pk_mul_f32 v[4:5], v[4:5], v[98:99] op_sel_hi:[1,0]
	v_pk_mul_f32 v[156:157], v[6:7], v[98:99] op_sel_hi:[1,0]
	s_waitcnt vmcnt(14)
	v_pk_fma_f32 v[6:7], v[10:11], v[4:5], v[18:19]
	v_pk_mul_f32 v[10:11], v[12:13], v[98:99] op_sel_hi:[1,0]
	v_pk_mul_f32 v[12:13], v[26:27], v[98:99] op_sel_hi:[1,0]
	v_pk_mul_f32 v[0:1], v[0:1], v[98:99] op_sel_hi:[1,0]
	v_pk_fma_f32 v[4:5], v[8:9], v[156:157], v[16:17]
	v_pk_mul_f32 v[8:9], v[14:15], v[98:99] op_sel_hi:[1,0]
	s_waitcnt vmcnt(10)
	v_pk_fma_f32 v[12:13], v[32:33], v[12:13], v[40:41]
	v_pk_mul_f32 v[32:33], v[2:3], v[98:99] op_sel_hi:[1,0]
	v_pk_mul_f32 v[14:15], v[24:25], v[98:99] op_sel_hi:[1,0]
	v_pk_mul_f32 v[16:17], v[38:39], v[98:99] op_sel_hi:[1,0]
	v_pk_mul_f32 v[18:19], v[36:37], v[98:99] op_sel_hi:[1,0]
	v_pk_fma_f32 v[10:11], v[22:23], v[10:11], v[30:31]
	v_pk_fma_f32 v[8:9], v[20:21], v[8:9], v[28:29]
	v_pk_fma_f32 v[14:15], v[34:35], v[14:15], v[42:43]
	s_waitcnt vmcnt(8)
	v_pk_fma_f32 v[18:19], v[46:47], v[18:19], v[54:55]
	v_pk_fma_f32 v[16:17], v[44:45], v[16:17], v[52:53]
	v_pk_mul_f32 v[20:21], v[50:51], v[98:99] op_sel_hi:[1,0]
	v_pk_mul_f32 v[22:23], v[48:49], v[98:99] op_sel_hi:[1,0]
	s_waitcnt vmcnt(6)
	v_pk_fma_f32 v[20:21], v[56:57], v[20:21], v[64:65]
	v_pk_fma_f32 v[22:23], v[58:59], v[22:23], v[66:67]
	v_pk_mul_f32 v[24:25], v[62:63], v[98:99] op_sel_hi:[1,0]
	v_pk_mul_f32 v[26:27], v[60:61], v[98:99] op_sel_hi:[1,0]
	s_waitcnt vmcnt(0)
	v_pk_fma_f32 v[2:3], v[90:91], v[0:1], v[94:95]
	v_pk_fma_f32 v[0:1], v[88:89], v[32:33], v[92:93]
	v_lshl_add_u64 v[32:33], v[154:155], 2, v[144:145]
	global_store_dwordx4 v[32:33], v[4:7], off
	global_store_dwordx4 v[32:33], v[8:11], off offset:1024
	global_store_dwordx4 v[32:33], v[12:15], off offset:2048
	global_store_dwordx4 v[32:33], v[16:19], off offset:3072
	v_add_co_u32_e32 v4, vcc, s27, v32
	v_pk_mul_f32 v[28:29], v[74:75], v[98:99] op_sel_hi:[1,0]
	s_nop 0
	v_addc_co_u32_e32 v5, vcc, 0, v33, vcc
	v_cmp_lt_i32_e32 vcc, s29, v96
	v_pk_mul_f32 v[30:31], v[72:73], v[98:99] op_sel_hi:[1,0]
	s_or_b64 s[12:13], vcc, s[12:13]
	v_pk_fma_f32 v[26:27], v[70:71], v[26:27], v[78:79]
	v_pk_fma_f32 v[24:25], v[68:69], v[24:25], v[76:77]
	v_pk_fma_f32 v[30:31], v[82:83], v[30:31], v[86:87]
	v_pk_fma_f32 v[28:29], v[80:81], v[28:29], v[84:85]
	global_store_dwordx4 v[4:5], v[20:23], off
	global_store_dwordx4 v[4:5], v[24:27], off offset:1024
	global_store_dwordx4 v[4:5], v[28:31], off offset:2048
	global_store_dwordx4 v[4:5], v[0:3], off offset:3072
	s_andn2_b64 exec, exec, s[12:13]
	s_cbranch_execz .LBB0_2451
